# GEMM loops: static raise of the wr==0 half at priority 3 instead of 1
# baseline (speedup 1.0000x reference)
.LBB0_171:
	s_or_b64 exec, exec, s[0:1]
	s_add_u32 s0, s30, 0xea00000
	s_addc_u32 s1, s31, 0
	s_add_u32 s3, s30, 0xce00000
	v_writelane_b32 v239, s3, 9
	s_addc_u32 s3, s31, 0
	v_writelane_b32 v239, s3, 10
	v_mov_b32_e32 v9, v176
	v_readlane_b32 s4, v239, 2
	s_ashr_i32 s3, s4, 31
	v_readlane_b32 s5, v239, 3
	v_writelane_b32 v239, s3, 11
	s_ashr_i32 s3, s2, 31
	s_waitcnt lgkmcnt(0)
	s_barrier
	s_cmpk_gt_i32 s2, 0x3ef
	s_nop 0
	v_readfirstlane_b32 s36, v9
	s_cbranch_scc1 .LBB0_183
	v_lshlrev_b32_e32 v0, 4, v9
	v_add_u32_e32 v1, 0x2000, v0
	v_ashrrev_i32_e32 v2, 31, v1
	v_lshrrev_b32_e32 v2, 22, v2
	v_add_u32_e32 v2, v1, v2
	v_ashrrev_i32_e32 v8, 10, v2
	v_mul_i32_i24_e32 v2, 0x400, v8
	v_sub_u32_e32 v1, v1, v2
	v_lshrrev_b32_e32 v2, 4, v1
	v_bitop3_b32 v1, v2, v1, 32 bitop3:0x6c
	v_ashrrev_i32_e32 v2, 31, v1
	v_lshrrev_b32_e32 v2, 26, v2
	v_add_u32_e32 v2, v1, v2
	v_lshlrev_b32_e32 v3, 3, v8
	v_ashrrev_i32_e32 v10, 6, v2
	v_and_b32_e32 v3, -16, v3
	v_add_u32_e32 v3, v10, v3
	v_and_b32_e32 v4, 3, v10
	s_mov_b32 s4, 0xfffe0
	v_lshrrev_b32_e32 v5, 2, v3
	v_lshlrev_b32_e32 v6, 1, v3
	v_and_b32_e32 v2, 0xc0, v2
	v_and_or_b32 v4, v3, s4, v4
	v_and_b32_e32 v5, 4, v5
	v_and_b32_e32 v6, 24, v6
	v_sub_u32_e32 v1, v1, v2
	v_mov_b32_e32 v2, 1
	v_or3_b32 v4, v4, v5, v6
	v_lshlrev_b32_e32 v5, 5, v8
	v_ashrrev_i16_sdwa v1, v2, sext(v1) dst_sel:DWORD dst_unused:UNUSED_PAD src0_sel:DWORD src1_sel:BYTE_0
	v_and_b32_e32 v5, 32, v5
	v_bfe_i32 v11, v1, 0, 16
	v_add_lshl_u32 v1, v5, v11, 1
	v_lshl_add_u32 v130, v4, 12, v1
	v_lshl_add_u32 v132, v3, 12, v1
	v_bfe_i32 v1, v9, 27, 1
	v_lshrrev_b32_e32 v1, 22, v1
	v_add_u32_e32 v1, v0, v1
	v_and_b32_e32 v1, 0xfffffc00, v1
	v_sub_u32_e32 v0, v0, v1
	v_lshrrev_b32_e32 v1, 4, v0
	v_bitop3_b32 v1, v1, v0, 32 bitop3:0x6c
	v_ashrrev_i32_e32 v0, 31, v0
	v_lshrrev_b32_e32 v0, 26, v0
	v_add_u32_e32 v0, v1, v0
	v_ashrrev_i32_e32 v12, 6, v0
	v_ashrrev_i32_e32 v0, 31, v9
	v_lshrrev_b32_e32 v0, 26, v0
	v_add_u32_e32 v0, v9, v0
	v_ashrrev_i32_e32 v13, 6, v0
	v_lshlrev_b32_e32 v0, 3, v13
	v_and_b32_e32 v0, -16, v0
	v_add_u32_e32 v0, v12, v0
	v_and_b32_e32 v3, 3, v12
	v_and_or_b32 v3, v0, s4, v3
	s_lshr_b32 s4, s3, 29
	s_add_i32 s4, s2, s4
	s_ashr_i32 s6, s36, 6
	s_ashr_i32 s7, s4, 3
	s_and_b32 s4, s4, -8
	s_ashr_i32 s5, s36, 8
	s_lshl_b32 s37, s6, 10
	s_sub_i32 s4, s2, s4
	s_cmp_lt_i32 s4, 0
	s_movk_i32 s38, 0x7f
	s_cselect_b32 s12, s38, 0x7e
	s_mul_i32 s4, s4, s12
	s_add_i32 s4, s4, s7
	v_lshrrev_b32_e32 v4, 2, v0
	v_lshlrev_b32_e32 v5, 1, v0
	s_mul_hi_i32 s7, s4, 0x92492493
	v_and_b32_e32 v4, 4, v4
	v_and_b32_e32 v5, 24, v5
	s_add_i32 s7, s7, s4
	v_or3_b32 v3, v3, v4, v5
	v_mul_i32_i24_e32 v5, 64, v12
	s_lshr_b32 s12, s7, 31
	s_ashr_i32 s7, s7, 7
	v_sub_u32_e32 v1, v1, v5
	s_add_i32 s7, s7, s12
	v_lshlrev_b32_e32 v4, 5, v13
	v_ashrrev_i16_sdwa v1, v2, sext(v1) dst_sel:DWORD dst_unused:UNUSED_PAD src0_sel:DWORD src1_sel:BYTE_0
	s_lshl_b32 s14, s7, 3
	v_and_b32_e32 v4, 32, v4
	v_bfe_i32 v14, v1, 0, 16
	s_sub_i32 s12, 36, s14
	s_mulk_i32 s7, 0xe0
	v_add_lshl_u32 v1, v4, v14, 1
	s_min_u32 s15, s12, 8
	s_sub_i32 s7, s4, s7
	v_lshl_add_u32 v134, v3, 12, v1
	s_sext_i32_i16 s4, s7
	v_cvt_f32_ubyte0_e32 v3, s15
	v_cvt_f32_i32_e32 v2, s4
	v_rcp_iflag_f32_e32 v4, v3
	v_lshl_add_u32 v136, v0, 12, v1
	s_ashr_i32 s4, s4, 30
	s_or_b32 s4, s4, 1
	v_mul_f32_e32 v0, v2, v4
	v_trunc_f32_e32 v0, v0
	v_fma_f32 v1, -v0, v3, v2
	v_cvt_i32_f32_e32 v0, v0
	v_cmp_ge_f32_e64 s[12:13], |v1|, v3
	s_and_b64 s[12:13], s[12:13], exec
	s_cselect_b32 s4, s4, 0
	v_readfirstlane_b32 s12, v0
	s_add_i32 s4, s12, s4
	s_mul_i32 s12, s4, s15
	s_sub_i32 s7, s7, s12
	s_sext_i32_i16 s7, s7
	s_add_i32 s20, s14, s7
	s_ashr_i32 s21, s20, 31
	s_bfe_i64 s[14:15], s[4:5], 0x100000
	s_lshl_b64 s[12:13], s[20:21], 20
	s_lshl_b64 s[14:15], s[14:15], 20
	v_readlane_b32 s7, v239, 9
	s_add_u32 s24, s7, s14
	v_readlane_b32 s7, v239, 10
	s_addc_u32 s25, s7, s15
	s_add_i32 s21, s37, 0
	s_add_i32 m0, s21, 0x10000
	v_mov_b32_e32 v135, 0
	global_load_lds_dwordx4 v134, s[24:25]
	s_add_i32 m0, s21, 0x12000
	s_add_u32 s22, s0, s12
	global_load_lds_dwordx4 v130, s[24:25]
	s_addc_u32 s23, s1, s13
	s_mov_b32 m0, s21
	s_add_i32 s39, s21, 0x2000
	global_load_lds_dwordx4 v136, s[22:23]
	s_mov_b32 m0, s39
	s_add_u32 s12, s24, 0x80000
	global_load_lds_dwordx4 v132, s[22:23]
	s_addc_u32 s13, s25, 0
	s_add_i32 m0, s21, 0x14000
	v_mov_b32_e32 v131, v135
	global_load_lds_dwordx4 v134, s[12:13]
	s_add_i32 m0, s21, 0x16000
	v_mov_b32_e32 v137, v135
	global_load_lds_dwordx4 v130, s[12:13]
	s_add_u32 s12, s22, 0x80000
	s_addc_u32 s13, s23, 0
	s_add_i32 s40, s21, 0x4000
	s_mov_b32 m0, s40
	s_add_i32 s41, s21, 0x6000
	global_load_lds_dwordx4 v136, s[12:13]
	s_mov_b32 m0, s41
	v_mov_b32_e32 v133, v135
	global_load_lds_dwordx4 v132, s[12:13]
	s_mov_b32 s97, s43
	s_mov_b32 s42, 0
	v_lshl_add_u64 v[6:7], s[24:25], 0, v[134:135]
	v_lshl_add_u64 v[4:5], s[24:25], 0, v[130:131]
	v_lshl_add_u64 v[2:3], s[22:23], 0, v[136:137]
	s_setprio 3
	s_cmp_lg_u32 s5, 1
	v_lshl_add_u64 v[0:1], s[22:23], 0, v[132:133]
	s_cbranch_scc1 .LBB0_174
	s_setprio 0
	s_barrier

.LBB0_678:
	s_or_b64 exec, exec, s[4:5]
	v_mov_b32_e32 v13, v176
	s_barrier
	s_mov_b32 s5, 0xfffe0
	v_ashrrev_i32_e32 v1, 31, v13
	v_lshrrev_b32_e32 v1, 26, v1
	v_add_u32_e32 v1, v13, v1
	v_ashrrev_i32_e32 v8, 6, v1
	v_bfe_i32 v1, v13, 27, 1
	v_lshlrev_b32_e32 v0, 4, v13
	v_lshrrev_b32_e32 v1, 22, v1
	v_add_u32_e32 v1, v0, v1
	v_and_b32_e32 v1, 0xfffffc00, v1
	v_sub_u32_e32 v1, v0, v1
	v_lshrrev_b32_e32 v2, 4, v1
	v_bitop3_b32 v2, v2, v1, 32 bitop3:0x6c
	v_ashrrev_i32_e32 v1, 31, v1
	v_lshrrev_b32_e32 v1, 26, v1
	v_add_u32_e32 v1, v2, v1
	v_ashrrev_i32_e32 v9, 6, v1
	v_lshlrev_b32_e32 v3, 3, v8
	v_mul_i32_i24_e32 v4, 64, v9
	v_and_b32_e32 v3, -16, v3
	v_sub_u32_e32 v2, v2, v4
	v_mov_b32_e32 v4, 1
	v_add_u32_e32 v1, v9, v3
	v_lshlrev_b32_e32 v3, 5, v8
	v_ashrrev_i16_sdwa v2, v4, sext(v2) dst_sel:DWORD dst_unused:UNUSED_PAD src0_sel:DWORD src1_sel:BYTE_0
	v_and_b32_e32 v3, 32, v3
	v_bfe_i32 v10, v2, 0, 16
	v_and_b32_e32 v6, 3, v9
	v_add_lshl_u32 v3, v3, v10, 1
	v_add_u32_e32 v0, 0x2000, v0
	v_lshlrev_b32_e32 v2, 1, v1
	v_lshrrev_b32_e32 v5, 2, v1
	v_and_or_b32 v6, v1, s5, v6
	v_lshl_add_u32 v128, v1, 12, v3
	v_ashrrev_i32_e32 v1, 31, v0
	v_lshrrev_b32_e32 v1, 22, v1
	v_add_u32_e32 v1, v0, v1
	v_ashrrev_i32_e32 v11, 10, v1
	v_mul_i32_i24_e32 v1, 0x400, v11
	v_sub_u32_e32 v0, v0, v1
	v_and_b32_e32 v2, 24, v2
	v_and_b32_e32 v5, 4, v5
	v_lshrrev_b32_e32 v1, 4, v0
	v_or3_b32 v2, v6, v5, v2
	v_bitop3_b32 v0, v1, v0, 32 bitop3:0x6c
	v_lshl_add_u32 v130, v2, 12, v3
	v_ashrrev_i32_e32 v2, 31, v0
	v_lshrrev_b32_e32 v2, 26, v2
	v_add_u32_e32 v2, v0, v2
	v_lshlrev_b32_e32 v1, 3, v11
	v_ashrrev_i32_e32 v12, 6, v2
	v_and_b32_e32 v2, 0xc0, v2
	s_sub_i32 s4, s68, s8
	v_and_b32_e32 v1, -16, v1
	v_sub_u32_e32 v0, v0, v2
	s_ashr_i32 s4, s4, 3
	v_readfirstlane_b32 s20, v13
	v_add_u32_e32 v1, v12, v1
	v_ashrrev_i16_sdwa v0, v4, sext(v0) dst_sel:DWORD dst_unused:UNUSED_PAD src0_sel:DWORD src1_sel:BYTE_0
	v_and_b32_e32 v4, 3, v12
	s_add_i32 s4, s4, 32
	s_and_b32 s22, s2, 7
	s_ashr_i32 s10, s20, 6
	v_and_or_b32 v4, v1, s5, v4
	s_mov_b32 s5, 0
	s_ashr_i32 s11, s20, 8
	s_lshl_b32 s16, s10, 10
	s_lshl_b64 s[12:13], s[4:5], 20
	s_lshl_b32 s14, s22, 20
	s_add_u32 s15, s30, s14
	s_addc_u32 s17, s31, 0
	s_add_u32 s6, s15, 0x13200000
	s_addc_u32 s7, s17, 0
	s_add_i32 s5, s16, 0
	s_add_i32 m0, s5, 0x10000
	v_lshlrev_b32_e32 v3, 5, v11
	v_bfe_i32 v14, v0, 0, 16
	v_lshlrev_b32_e32 v0, 1, v1
	v_lshrrev_b32_e32 v2, 2, v1
	global_load_lds_dwordx4 v130, s[6:7]
	s_add_i32 m0, s5, 0x12000
	v_and_b32_e32 v3, 32, v3
	v_and_b32_e32 v0, 24, v0
	v_and_b32_e32 v2, 4, v2
	s_add_u32 s21, s30, s12
	v_or3_b32 v0, v4, v2, v0
	v_add_lshl_u32 v2, v3, v14, 1
	s_addc_u32 s24, s31, s13
	v_lshl_add_u32 v134, v0, 12, v2
	s_add_u32 s8, s21, 0x10e00000
	global_load_lds_dwordx4 v134, s[6:7]
	s_addc_u32 s9, s24, 0
	s_mov_b32 m0, s5
	s_add_i32 s23, s5, 0x2000
	v_lshl_add_u32 v132, v1, 12, v2
	global_load_lds_dwordx4 v128, s[8:9]
	s_mov_b32 m0, s23
	s_add_u32 s18, s15, 0x13280000
	global_load_lds_dwordx4 v132, s[8:9]
	s_addc_u32 s19, s17, 0
	s_add_i32 m0, s5, 0x14000
	v_mov_b32_e32 v131, 0
	global_load_lds_dwordx4 v130, s[18:19]
	s_add_i32 m0, s5, 0x16000
	v_mov_b32_e32 v135, v131
	global_load_lds_dwordx4 v134, s[18:19]
	s_add_u32 s18, s21, 0x10e80000
	s_addc_u32 s19, s24, 0
	s_add_i32 s24, s5, 0x4000
	s_mov_b32 m0, s24
	s_add_i32 s25, s5, 0x6000
	global_load_lds_dwordx4 v128, s[18:19]
	s_mov_b32 m0, s25
	v_mov_b32_e32 v129, v131
	global_load_lds_dwordx4 v132, s[18:19]
	v_mov_b32_e32 v133, v131
	v_lshl_add_u64 v[6:7], s[6:7], 0, v[130:131]
	v_lshl_add_u64 v[4:5], s[6:7], 0, v[134:135]
	v_lshl_add_u64 v[2:3], s[8:9], 0, v[128:129]
	s_setprio 3
	s_cmp_lg_u32 s11, 1
	v_lshl_add_u64 v[0:1], s[8:9], 0, v[132:133]
	s_cbranch_scc1 .LBB0_680
	s_setprio 0
	s_barrier

.LBB0_856:
	s_add_u32 s8, s30, 0x17d29000
	s_addc_u32 s9, s31, 0
	s_andn2_b64 vcc, exec, s[4:5]
	s_cbranch_vccnz .LBB0_888
	v_ashrrev_i32_e32 v1, 31, v9
	v_lshrrev_b32_e32 v1, 26, v1
	v_add_u32_e32 v1, v9, v1
	v_ashrrev_i32_e32 v8, 6, v1
	v_bfe_i32 v1, v9, 27, 1
	v_lshlrev_b32_e32 v0, 4, v9
	v_lshrrev_b32_e32 v1, 22, v1
	v_add_u32_e32 v1, v0, v1
	v_and_b32_e32 v1, 0xfffffc00, v1
	v_sub_u32_e32 v1, v0, v1
	v_lshrrev_b32_e32 v2, 4, v1
	v_bitop3_b32 v2, v2, v1, 32 bitop3:0x6c
	v_ashrrev_i32_e32 v1, 31, v1
	v_lshrrev_b32_e32 v1, 26, v1
	v_add_u32_e32 v1, v2, v1
	v_ashrrev_i32_e32 v10, 6, v1
	v_lshlrev_b32_e32 v3, 3, v8
	v_mul_i32_i24_e32 v4, 64, v10
	v_and_b32_e32 v3, -16, v3
	v_sub_u32_e32 v2, v2, v4
	v_mov_b32_e32 v4, 1
	v_add_u32_e32 v1, v10, v3
	v_lshlrev_b32_e32 v3, 5, v8
	v_ashrrev_i16_sdwa v2, v4, sext(v2) dst_sel:DWORD dst_unused:UNUSED_PAD src0_sel:DWORD src1_sel:BYTE_0
	v_and_b32_e32 v3, 32, v3
	v_bfe_i32 v11, v2, 0, 16
	v_and_b32_e32 v6, 3, v10
	s_mov_b32 s5, 0xfffe0
	v_add_lshl_u32 v3, v3, v11, 1
	v_add_u32_e32 v0, 0x2000, v0
	v_lshlrev_b32_e32 v2, 1, v1
	v_lshrrev_b32_e32 v5, 2, v1
	v_and_or_b32 v6, v1, s5, v6
	v_lshl_add_u32 v182, v1, 12, v3
	v_ashrrev_i32_e32 v1, 31, v0
	v_lshrrev_b32_e32 v1, 22, v1
	v_add_u32_e32 v1, v0, v1
	v_ashrrev_i32_e32 v12, 10, v1
	v_mul_i32_i24_e32 v1, 0x400, v12
	v_sub_u32_e32 v0, v0, v1
	v_and_b32_e32 v2, 24, v2
	v_and_b32_e32 v5, 4, v5
	v_lshrrev_b32_e32 v1, 4, v0
	v_or3_b32 v2, v6, v5, v2
	v_bitop3_b32 v0, v1, v0, 32 bitop3:0x6c
	v_lshl_add_u32 v184, v2, 12, v3
	v_ashrrev_i32_e32 v2, 31, v0
	v_lshrrev_b32_e32 v2, 26, v2
	s_add_u32 s35, s30, 0x10e00000
	v_add_u32_e32 v2, v0, v2
	s_addc_u32 s38, s31, 0
	v_lshlrev_b32_e32 v1, 3, v12
	v_ashrrev_i32_e32 v13, 6, v2
	v_and_b32_e32 v2, 0xc0, v2
	s_add_u32 s39, s30, 0x13200000
	v_and_b32_e32 v1, -16, v1
	v_sub_u32_e32 v0, v0, v2
	s_addc_u32 s40, s31, 0
	s_ashr_i32 s4, s33, 6
	v_add_u32_e32 v1, v13, v1
	v_ashrrev_i16_sdwa v0, v4, sext(v0) dst_sel:DWORD dst_unused:UNUSED_PAD src0_sel:DWORD src1_sel:BYTE_0
	v_and_b32_e32 v4, 3, v13
	s_ashr_i32 s13, s12, 31
	s_ashr_i32 s11, s10, 31
	v_and_or_b32 v4, v1, s5, v4
	s_ashr_i32 s5, s33, 8
	s_lshl_b32 s41, s4, 10
	s_lshl_b64 s[6:7], s[12:13], 20
	s_lshl_b64 s[14:15], s[10:11], 20
	s_add_u32 s26, s39, s14
	v_lshlrev_b32_e32 v3, 5, v12
	v_bfe_i32 v14, v0, 0, 16
	v_lshlrev_b32_e32 v0, 1, v1
	v_lshrrev_b32_e32 v2, 2, v1
	s_addc_u32 s27, s40, s15
	s_add_i32 s11, s41, 0
	v_and_b32_e32 v3, 32, v3
	v_and_b32_e32 v0, 24, v0
	v_and_b32_e32 v2, 4, v2
	s_add_i32 m0, s11, 0x10000
	v_or3_b32 v0, v4, v2, v0
	v_add_lshl_u32 v2, v3, v14, 1
	global_load_lds_dwordx4 v184, s[26:27]
	s_add_i32 m0, s11, 0x12000
	v_lshl_add_u32 v188, v0, 12, v2
	s_add_u32 s24, s35, s6
	global_load_lds_dwordx4 v188, s[26:27]
	s_addc_u32 s25, s38, s7
	s_mov_b32 m0, s11
	s_add_i32 s42, s11, 0x2000
	v_lshl_add_u32 v186, v1, 12, v2
	global_load_lds_dwordx4 v182, s[24:25]
	s_mov_b32 m0, s42
	s_add_u32 s6, s26, 0x80000
	global_load_lds_dwordx4 v186, s[24:25]
	s_addc_u32 s7, s27, 0
	s_add_i32 m0, s11, 0x14000
	v_mov_b32_e32 v185, 0
	global_load_lds_dwordx4 v184, s[6:7]
	s_add_i32 m0, s11, 0x16000
	v_mov_b32_e32 v189, v185
	global_load_lds_dwordx4 v188, s[6:7]
	s_add_u32 s6, s24, 0x80000
	s_addc_u32 s7, s25, 0
	s_add_i32 s43, s11, 0x4000
	s_mov_b32 m0, s43
	s_add_i32 s44, s11, 0x6000
	global_load_lds_dwordx4 v182, s[6:7]
	s_mov_b32 m0, s44
	v_mov_b32_e32 v183, v185
	global_load_lds_dwordx4 v186, s[6:7]
	v_mov_b32_e32 v187, v185
	s_movk_i32 s45, 0x2000
	s_mov_b32 s13, 0
	v_lshl_add_u64 v[6:7], s[26:27], 0, v[184:185]
	v_lshl_add_u64 v[4:5], s[26:27], 0, v[188:189]
	v_lshl_add_u64 v[2:3], s[24:25], 0, v[182:183]
	s_setprio 3
	s_cmp_lg_u32 s5, 1
	v_lshl_add_u64 v[0:1], s[24:25], 0, v[186:187]
	s_cbranch_scc1 .LBB0_859
	s_setprio 0
	s_barrier

.Lt5_sel:
	s_ashr_i32 s17, s16, 31
	s_bfe_i64 s[12:13], s[4:5], 0x100000
	s_lshl_b64 s[10:11], s[16:17], 20
	s_lshl_b64 s[12:13], s[12:13], 20
	v_readlane_b32 s14, v239, 7
	v_readlane_b32 s15, v239, 8
	s_add_u32 s20, s14, s12
	s_addc_u32 s21, s15, s13
	s_add_i32 s17, s25, 0
	s_add_i32 m0, s17, 0x10000
	v_mov_b32_e32 v133, 0
	global_load_lds_dwordx4 v132, s[20:21]
	s_add_i32 m0, s17, 0x12000
	s_add_u32 s18, s0, s10
	global_load_lds_dwordx4 v128, s[20:21]
	s_addc_u32 s19, s1, s11
	s_mov_b32 m0, s17
	s_add_i32 s27, s17, 0x2000
	global_load_lds_dwordx4 v134, s[18:19]
	s_mov_b32 m0, s27
	s_add_u32 s10, s20, 0x80000
	global_load_lds_dwordx4 v130, s[18:19]
	s_addc_u32 s11, s21, 0
	s_add_i32 m0, s17, 0x14000
	v_mov_b32_e32 v129, v133
	global_load_lds_dwordx4 v132, s[10:11]
	s_add_i32 m0, s17, 0x16000
	v_mov_b32_e32 v135, v133
	global_load_lds_dwordx4 v128, s[10:11]
	s_add_u32 s10, s18, 0x80000
	s_addc_u32 s11, s19, 0
	s_add_i32 s33, s17, 0x4000
	s_mov_b32 m0, s33
	s_add_i32 s35, s17, 0x6000
	global_load_lds_dwordx4 v134, s[10:11]
	s_mov_b32 m0, s35
	v_mov_b32_e32 v131, v133
	global_load_lds_dwordx4 v130, s[10:11]
	s_lshl_b32 s36, s97, 8
	v_lshl_add_u64 v[6:7], s[20:21], 0, v[132:133]
	v_lshl_add_u64 v[4:5], s[20:21], 0, v[128:129]
	v_lshl_add_u64 v[2:3], s[18:19], 0, v[134:135]
	s_setprio 3
	s_cmp_lg_u32 s6, 1
	v_lshl_add_u64 v[0:1], s[18:19], 0, v[130:131]
	s_cbranch_scc1 .LBB0_939
	s_setprio 0
	s_barrier

.LBB0_1069:
	s_or_b64 exec, exec, s[0:1]
	v_mov_b32_e32 v16, v176
	s_waitcnt lgkmcnt(0)
	s_barrier
	s_cmpk_lt_i32 s2, 0x240
	v_readfirstlane_b32 s18, v16
	s_cbranch_scc0 .LBB0_1089
	v_lshlrev_b32_e32 v0, 4, v16
	v_add_u32_e32 v1, 0x2000, v0
	v_ashrrev_i32_e32 v2, 31, v1
	v_lshrrev_b32_e32 v2, 22, v2
	v_add_u32_e32 v2, v1, v2
	v_ashrrev_i32_e32 v8, 10, v2
	v_mul_i32_i24_e32 v2, 0x400, v8
	v_sub_u32_e32 v1, v1, v2
	v_lshrrev_b32_e32 v2, 4, v1
	v_bitop3_b32 v1, v2, v1, 32 bitop3:0x6c
	v_ashrrev_i32_e32 v2, 31, v1
	v_lshrrev_b32_e32 v2, 26, v2
	v_add_u32_e32 v2, v1, v2
	v_lshlrev_b32_e32 v3, 3, v8
	v_ashrrev_i32_e32 v9, 6, v2
	v_and_b32_e32 v3, -16, v3
	v_add_u32_e32 v3, v9, v3
	v_and_b32_e32 v4, 3, v9
	s_mov_b32 s5, 0x7fffe0
	v_lshrrev_b32_e32 v5, 2, v3
	v_lshlrev_b32_e32 v6, 1, v3
	v_and_b32_e32 v2, 0xc0, v2
	v_and_or_b32 v4, v3, s5, v4
	v_and_b32_e32 v5, 4, v5
	v_and_b32_e32 v6, 24, v6
	v_sub_u32_e32 v1, v1, v2
	v_mov_b32_e32 v2, 1
	v_or3_b32 v4, v4, v5, v6
	v_lshlrev_b32_e32 v5, 5, v8
	v_ashrrev_i16_sdwa v1, v2, sext(v1) dst_sel:DWORD dst_unused:UNUSED_PAD src0_sel:DWORD src1_sel:BYTE_0
	s_movk_i32 s4, 0x1600
	v_and_b32_e32 v10, 32, v5
	v_bfe_i32 v11, v1, 0, 16
	v_mul_u32_u24_e32 v4, 0x1600, v4
	v_add_u32_e32 v1, v10, v11
	v_mul_lo_u32 v3, v3, s4
	v_add_lshl_u32 v128, v4, v1, 1
	v_add_lshl_u32 v130, v1, v3, 1
	v_bfe_i32 v1, v16, 27, 1
	v_lshrrev_b32_e32 v1, 22, v1
	v_add_u32_e32 v1, v0, v1
	v_and_b32_e32 v1, 0xfffffc00, v1
	v_sub_u32_e32 v0, v0, v1
	v_lshrrev_b32_e32 v1, 4, v0
	v_bitop3_b32 v1, v1, v0, 32 bitop3:0x6c
	v_ashrrev_i32_e32 v0, 31, v0
	v_lshrrev_b32_e32 v0, 26, v0
	v_add_u32_e32 v0, v1, v0
	v_ashrrev_i32_e32 v12, 6, v0
	v_ashrrev_i32_e32 v0, 31, v16
	v_lshrrev_b32_e32 v0, 26, v0
	v_add_u32_e32 v0, v16, v0
	v_ashrrev_i32_e32 v13, 6, v0
	v_lshlrev_b32_e32 v0, 3, v13
	v_and_b32_e32 v0, -16, v0
	v_add_u32_e32 v0, v12, v0
	v_and_b32_e32 v3, 3, v12
	v_and_or_b32 v3, v0, s5, v3
	s_ashr_i32 s1, s18, 6
	s_ashr_i32 s0, s18, 8
	s_lshl_b32 s19, s1, 10
	v_lshrrev_b32_e32 v4, 2, v0
	v_lshlrev_b32_e32 v5, 1, v0
	v_and_b32_e32 v4, 4, v4
	v_and_b32_e32 v5, 24, v5
	s_and_b32 s5, s2, 7
	s_mul_i32 s100, s5, 50
	s_add_i32 s101, s100, 48
	s_add_i32 s100, s100, -2
	s_max_i32 s100, s100, 0
	s_min_i32 s101, s101, 0x18c

	s_mul_i32 s6, s100, 0x5d2
	s_lshr_b32 s6, s6, 16
	s_mul_i32 s7, s6, 44
	s_sub_i32 s8, s100, s7
	s_add_i32 s7, s7, 44
	s_min_i32 s7, s7, s101
	s_sub_i32 s7, s7, s100
	s_cmp_eq_u32 s7, 44
	s_cselect_b32 s7, 42, s7
	s_add_i32 s100, s100, s7

	s_lshl_b32 s98, s7, 1
	s_add_i32 s98, s98, -4
	s_cmp_lg_u32 s8, 0
	s_cselect_b32 s43, 1, 0
	s_lshr_b32 s9, s2, 6
	s_lshl_b32 s6, s6, 2
	s_add_i32 s42, s6, s9
	s_bfe_u32 s44, s2, 0x30003
	s_lshl_b32 s7, s8, 8
	s_mov_b32 s8, 0
	v_or3_b32 v3, v3, v4, v5
	v_lshlrev_b32_e32 v4, 5, v13
	s_mul_i32 s9, s44, 0x2c0000
	v_and_b32_e32 v14, 32, v4
	v_mul_i32_i24_e32 v4, 64, v12
	s_ashr_i32 s10, s9, 31
	v_readlane_b32 s12, v238, 23
	v_sub_u32_e32 v1, v1, v4
	v_readlane_b32 s13, v238, 24
	s_add_u32 s9, s12, s9
	v_ashrrev_i16_sdwa v1, v2, sext(v1) dst_sel:DWORD dst_unused:UNUSED_PAD src0_sel:DWORD src1_sel:BYTE_0
	s_addc_u32 s10, s13, s10
	v_bfe_i32 v15, v1, 0, 16
	s_add_u32 s12, s9, s7
	v_mul_u32_u24_e32 v3, 0x1600, v3
	v_add_u32_e32 v1, v14, v15
	s_addc_u32 s13, s10, s8
	s_add_i32 s21, s19, 0
	v_add_lshl_u32 v132, v3, v1, 1
	s_add_i32 m0, s21, 0x10000
	s_mul_i32 s6, s42, 0x2c0000
	global_load_lds_dwordx4 v132, s[12:13]
	s_add_i32 m0, s21, 0x12000
	v_readlane_b32 s9, v239, 9
	s_mul_hi_i32 s5, s42, 0x2c0000
	s_add_u32 s6, s9, s6
	v_readlane_b32 s9, v239, 10
	s_addc_u32 s5, s9, s5
	v_mul_lo_u32 v0, v0, s4
	s_add_u32 s10, s6, s7
	v_add_lshl_u32 v134, v1, v0, 1
	global_load_lds_dwordx4 v128, s[12:13]
	s_addc_u32 s11, s5, s8
	s_mov_b32 m0, s21
	s_add_i32 s22, s21, 0x2000
	global_load_lds_dwordx4 v134, s[10:11]
	s_mov_b32 m0, s22
	s_add_u32 s6, s12, 0x160000
	global_load_lds_dwordx4 v130, s[10:11]
	s_addc_u32 s7, s13, 0
	s_add_i32 m0, s21, 0x14000
	v_mov_b32_e32 v133, 0
	global_load_lds_dwordx4 v132, s[6:7]
	s_add_i32 m0, s21, 0x16000
	v_mov_b32_e32 v129, v133
	global_load_lds_dwordx4 v128, s[6:7]
	s_add_u32 s6, s10, 0x160000
	s_addc_u32 s7, s11, 0
	s_add_i32 s23, s21, 0x4000
	s_mov_b32 m0, s23
	s_add_i32 s24, s21, 0x6000
	global_load_lds_dwordx4 v134, s[6:7]
	s_mov_b32 m0, s24
	v_mov_b32_e32 v135, v133
	global_load_lds_dwordx4 v130, s[6:7]
	v_mov_b32_e32 v131, v133
	s_movk_i32 s25, 0x2000
	s_mov_b32 s26, 0
	v_lshl_add_u64 v[6:7], s[12:13], 0, v[132:133]
	v_lshl_add_u64 v[4:5], s[12:13], 0, v[128:129]
	v_lshl_add_u64 v[2:3], s[10:11], 0, v[134:135]
	v_lshl_add_u64 v[0:1], s[10:11], 0, v[130:131]
	s_setprio 3
	s_cmp_lg_u32 s0, 1
	s_mov_b32 s5, 0x16000
	s_cbranch_scc1 .LBB0_1072
	s_setprio 0
	s_barrier
